# plus work-queue pop prefetch in mixer A and MLA (next item's atomic issued before the tile loop, counted vmcnt at the pop) and prefetch-friendly vmcnt placement in their tile loops
# baseline (speedup 1.0000x reference)
.LBB0_1096:
	s_mov_b32 s98, 0
	s_add_i32 s8, s56, s6
	s_and_b32 s57, s8, 7
	s_lshl_b32 s8, s57, 2
	s_add_u32 s14, s24, s8
	s_addc_u32 s15, s25, 0
	s_branch .LBB0_1100

.LBB0_1100:
	s_and_b64 vcc, exec, s[4:5]
	s_barrier
	s_cbranch_vccnz .LBB0_1106
	v_mbcnt_lo_u32_b32 v0, -1, 0
	v_mbcnt_hi_u32_b32 v0, -1, v0
	s_nop 0
	v_cmp_eq_u32_e32 vcc, 0, v0
	s_and_saveexec_b64 s[8:9], vcc
	s_cbranch_execz .LBB0_1105
	s_mov_b64 s[18:19], exec
	v_mbcnt_lo_u32_b32 v0, s18, 0
	v_mbcnt_hi_u32_b32 v0, s19, v0
	v_cmp_eq_u32_e32 vcc, 0, v0
	s_and_saveexec_b64 s[16:17], vcc
	s_cbranch_execz .LBB0_1104
	s_cmp_lg_u32 s98, 0
	s_cbranch_scc1 .Lpfq_have_mixa
	s_bcnt1_i32_b64 s12, s[18:19]
	v_mov_b32_e32 v2, s12
	global_atomic_add v2, v1, v2, s[14:15] offset:64 sc0
	s_waitcnt vmcnt(0)
	s_branch .Lpfq_join_mixa
.Lpfq_have_mixa:
	s_waitcnt vmcnt(8)
	v_mov_b32_e32 v2, v232
.Lpfq_join_mixa:
	s_mov_b32 s98, 0
.LBB0_1104:
	s_or_b64 exec, exec, s[16:17]
	v_readfirstlane_b32 s12, v2
	v_mov_b32_e32 v2, s7
	s_nop 0
	v_add_u32_e32 v0, s12, v0
	ds_write_b32 v2, v0

.LBB0_1106:
	s_waitcnt lgkmcnt(0)
	s_barrier
	ds_read_b32 v0, v136
	s_mov_b64 s[8:9], -1
	s_waitcnt lgkmcnt(0)
	v_cmp_lt_i32_e32 vcc, s29, v0
	v_readfirstlane_b32 s12, v0
	s_cbranch_vccnz .LBB0_1099
	s_lshl_b32 s8, s12, 3
	s_and_b32 s8, s8, 8
	s_or_b32 s8, s8, s57
	s_lshl_b32 s8, s8, 6
	s_ashr_i32 s12, s12, 1
	s_add_i32 s16, s8, s12
	s_bfe_u32 s9, s16, 0x10006
	s_lshl_b32 s8, s9, 3
	s_add_i32 s8, s8, s93
	v_mbcnt_lo_u32_b32 v4, -1, 0
	v_mbcnt_hi_u32_b32 v4, -1, v4
	s_lshl_b32 s12, s12, 5
	v_lshl_add_u32 v2, s8, 7, v4
	v_ashrrev_i32_e32 v3, 31, v2
	v_lshl_add_u64 v[2:3], v[2:3], 2, s[64:65]
	global_load_dword v0, v[2:3], off
	global_load_dword v5, v[2:3], off offset:256
	s_and_b32 s68, s12, 0x7e0
	s_bfe_u32 s12, s12, 0x50006
	v_sub_u32_e64 v7, s68, v138 clamp
	s_lshl_b32 s17, -2, s12
	v_readfirstlane_b32 s18, v7
	s_not_b32 s19, s17
	s_ashr_i32 s17, s16, 7
	s_lshr_b32 s16, s18, 6
	s_lshl_b32 s66, s8, 6
	v_and_b32_e32 v2, 31, v4
	s_cmp_lg_u32 s12, 31
	v_or_b32_e32 v101, s68, v2
	s_cselect_b32 s12, s19, -1
	s_lshl_b32 s16, -1, s16
	v_ashrrev_i32_e32 v3, 5, v4
	v_lshl_or_b32 v98, s17, 11, v101
	s_and_b32 s16, s16, s12
	v_lshl_add_u32 v6, v4, 2, s3
	v_ashrrev_i32_e32 v99, 31, v98
	s_cmp_eq_u32 s16, 0
	v_lshlrev_b32_e32 v100, 2, v3
	s_waitcnt vmcnt(0)
	ds_write2st64_b32 v6, v0, v5 offset1:1
	s_cbranch_scc1 .LBB0_1097
	s_lshl_b32 s12, s66, 1
	s_mul_hi_i32 s18, s17, 0xd00000
	s_mul_i32 s17, s17, 0xd00000
	s_add_u32 s17, s50, s17
	s_addc_u32 s19, s51, s18
	s_lshl_b32 s9, s9, 7
	s_add_u32 s18, s17, s9
	s_addc_u32 s19, s19, 0
	s_lshl_b32 s8, s8, 2
	v_mov_b32_e32 v0, s8
	global_load_dword v21, v0, s[10:11]
	v_add_u32_e32 v0, s91, v4
	s_ff1_i32_b32 s8, s16
	s_add_i32 s9, s16, -1
	v_ashrrev_i32_e32 v22, 3, v0
	v_lshlrev_b32_e32 v0, 4, v4
	s_and_b32 s9, s9, s16
	s_mul_i32 s16, s8, 0x68000
	v_and_b32_e32 v139, 0x70, v0
	v_mul_lo_u32 v0, v22, s30
	s_add_u32 s16, s18, s16
	v_or_b32_e32 v0, v0, v139
	s_addc_u32 s17, s19, 0
	v_mov_b64_e32 v[8:9], s[50:51]
	global_load_dwordx4 v[12:15], v0, s[16:17] offset:2048
	global_load_dwordx4 v[16:19], v0, s[16:17] offset:2304
	v_lshlrev_b32_e32 v10, 3, v3
	v_mad_i64_i32 v[8:9], s[16:17], v98, s30, v[8:9]
	v_ashrrev_i32_e32 v11, 31, v10
	v_lshl_add_u64 v[8:9], v[8:9], 0, s[12:13]
	v_lshl_add_u64 v[8:9], v[10:11], 1, v[8:9]
	global_load_dwordx4 v[66:69], v[8:9], off
	global_load_dwordx4 v[70:73], v[8:9], off offset:32
	global_load_dwordx4 v[74:77], v[8:9], off offset:64
	global_load_dwordx4 v[78:81], v[8:9], off offset:96
	v_lshrrev_b32_e32 v20, 2, v4
	v_mul_lo_u32 v163, v22, s35
	v_lshlrev_b32_e32 v23, 1, v4
	v_and_or_b32 v11, v20, 3, v100
	v_add3_u32 v20, 0, v163, v139
	v_lshlrev_b32_e32 v24, 3, v4
	v_lshlrev_b32_e32 v25, 7, v3
	v_lshlrev_b32_e32 v26, 2, v2
	v_and_b32_e32 v159, 32, v23
	v_mul_lo_u32 v164, v22, s34
	v_mul_u32_u24_e32 v140, 0x90, v2
	v_lshlrev_b32_e32 v141, 4, v3
	v_mov_b32_e32 v2, v1
	v_mov_b32_e32 v3, v1
	v_mov_b32_e32 v4, v1
	v_mov_b32_e32 v5, v1
	v_mov_b32_e32 v6, v1
	v_mov_b32_e32 v7, v1
	v_mov_b32_e32 v8, v1
	v_mov_b32_e32 v9, v1
	v_mov_b32_e32 v10, v1
	v_and_b32_e32 v160, 24, v24
	v_bitop3_b32 v161, v25, s46, v26 bitop3:0x36
	v_mul_lo_u32 v162, v11, s34
	v_mov_b32_e32 v11, v1
	v_mov_b32_e32 v24, v1
	v_mov_b32_e32 v25, v1
	v_mov_b32_e32 v26, v1
	v_mov_b32_e32 v27, v1
	v_mov_b32_e32 v28, v1
	v_mov_b32_e32 v29, v1
	v_mov_b32_e32 v30, v1
	v_mov_b32_e32 v31, v1
	v_lshl_add_u64 v[102:103], s[18:19], 0, v[0:1]
	v_mov_b32_e32 v0, v1
	v_mov_b32_e32 v104, 0
	s_mov_b32 s67, 0
	v_sub_u32_e32 v142, 0, v100
	v_subrev_u32_e32 v143, 32, v101
	v_not_b32_e32 v144, v100
	v_xor_b32_e32 v145, -2, v100
	v_xor_b32_e32 v146, -3, v100
	v_sub_u32_e32 v147, -8, v100
	v_sub_u32_e32 v148, -9, v100
	v_sub_u32_e32 v149, -10, v100
	v_sub_u32_e32 v150, -11, v100
	v_sub_u32_e32 v151, -16, v100
	v_sub_u32_e32 v152, 0xffffffef, v100
	v_sub_u32_e32 v153, 0xffffffee, v100
	v_sub_u32_e32 v154, 0xffffffed, v100
	v_sub_u32_e32 v155, 0xffffffe8, v100
	v_sub_u32_e32 v156, 0xffffffe7, v100
	v_sub_u32_e32 v157, 0xffffffe6, v100
	v_sub_u32_e32 v158, 0xffffffe5, v100
	s_addk_i32 s68, 0xff51
	v_mov_b32_e32 v165, 1.0
	v_mov_b32_e32 v105, v104
	v_mov_b32_e32 v106, v104
	s_waitcnt vmcnt(6)
	v_mad_u64_u32 v[22:23], s[16:17], v22, 48, v[20:21]
	v_mul_f32_e32 v166, 0x3fb8aa3b, v21
	s_waitcnt vmcnt(5)
	ds_write_b128 v20, v[12:15]
	s_waitcnt vmcnt(0)
	ds_write_b128 v22, v[16:19] offset:9216
	v_mov_b32_e32 v12, v1
	v_mov_b32_e32 v13, v1
	v_mov_b32_e32 v14, v1
	v_mov_b32_e32 v15, v1
	v_mov_b32_e32 v16, v1
	v_mov_b32_e32 v17, v1
	v_mov_b32_e32 v18, v1
	v_mov_b32_e32 v19, v1
	v_mov_b32_e32 v20, v1
	v_mov_b32_e32 v21, v1
	v_mov_b32_e32 v22, v1
	v_mov_b32_e32 v23, v1
	v_mov_b64_e32 v[32:33], v[30:31]
	v_mov_b64_e32 v[30:31], v[28:29]
	v_mov_b64_e32 v[28:29], v[26:27]
	v_mov_b64_e32 v[26:27], v[24:25]
	v_mov_b64_e32 v[24:25], v[22:23]
	v_mov_b64_e32 v[22:23], v[20:21]
	v_mov_b64_e32 v[20:21], v[18:19]
	v_mov_b64_e32 v[18:19], v[16:17]
	v_mov_b64_e32 v[16:17], v[14:15]
	v_mov_b64_e32 v[14:15], v[12:13]
	v_mov_b64_e32 v[12:13], v[10:11]
	v_mov_b64_e32 v[10:11], v[8:9]
	v_mov_b64_e32 v[8:9], v[6:7]
	v_mov_b64_e32 v[6:7], v[4:5]
	v_mov_b64_e32 v[4:5], v[2:3]
	v_mov_b64_e32 v[2:3], v[0:1]
	v_mov_b32_e32 v107, v104
	v_mov_b32_e32 v108, v104
	v_mov_b32_e32 v109, v104
	v_mov_b32_e32 v110, v104
	v_mov_b32_e32 v111, v104
	v_mov_b32_e32 v112, v104
	v_mov_b32_e32 v113, v104
	v_mov_b32_e32 v114, v104
	v_mov_b32_e32 v115, v104
	v_mov_b32_e32 v116, v104
	v_mov_b32_e32 v117, v104
	v_mov_b32_e32 v118, v104
	v_mov_b32_e32 v119, v104
	v_mov_b32_e32 v120, v104
	v_mov_b32_e32 v121, v104
	v_mov_b32_e32 v122, v104
	v_mov_b32_e32 v123, v104
	v_mov_b32_e32 v124, v104
	v_mov_b32_e32 v125, v104
	v_mov_b32_e32 v126, v104
	v_mov_b32_e32 v127, v104
	v_mov_b32_e32 v128, v104
	v_mov_b32_e32 v129, v104
	v_mov_b32_e32 v130, v104
	v_mov_b32_e32 v131, v104
	v_mov_b32_e32 v132, v104
	v_mov_b32_e32 v133, v104
	v_mov_b32_e32 v134, v104
	v_mov_b32_e32 v135, v104
	s_mov_b32 s69, s8
	s_waitcnt lgkmcnt(0)
	s_barrier
	s_and_b64 vcc, exec, s[4:5]
	s_cbranch_vccnz .Lpfq_skip_mixa
	v_mbcnt_lo_u32_b32 v231, -1, 0
	v_mbcnt_hi_u32_b32 v231, -1, v231
	v_cmp_eq_u32_e32 vcc, 0, v231
	s_and_saveexec_b64 s[100:101], vcc
	v_mov_b32_e32 v232, 1
	global_atomic_add v232, v231, v232, s[14:15] offset:64 sc0
	s_mov_b64 exec, s[100:101]
	s_mov_b32 s98, 1
.Lpfq_skip_mixa:
.LBB0_1109:
	s_cmp_eq_u32 s9, 0
	s_cselect_b64 s[16:17], -1, 0
	s_cmp_lg_u32 s9, 0
	s_cselect_b64 s[18:19], -1, 0
	s_and_b64 vcc, exec, s[16:17]
	s_mov_b32 s12, 0
	s_cbranch_vccnz .LBB0_1111
	s_ff1_i32_b32 s69, s9
	s_mul_i32 s12, s69, 0x68000
	v_lshl_add_u64 v[34:35], v[102:103], 0, s[12:13]
	global_load_dwordx4 v[82:85], v[34:35], off offset:2048
	global_load_dwordx4 v[86:89], v[34:35], off offset:2304
	s_add_i32 s12, s9, -1
	s_and_b32 s12, s12, s9

.LBB0_2616:
	s_mov_b32 s98, 0
	s_add_i32 s6, s49, s12
	s_and_b32 s56, s6, 7
	s_lshl_b32 s6, s56, 2
	s_add_u32 s14, s24, s6
	s_addc_u32 s15, s25, 0
	s_branch .LBB0_2620

.LBB0_2620:
	s_and_b64 vcc, exec, s[4:5]
	s_barrier
	s_cbranch_vccnz .LBB0_2626
	v_mbcnt_lo_u32_b32 v0, -1, 0
	v_mbcnt_hi_u32_b32 v0, -1, v0
	s_nop 0
	v_cmp_eq_u32_e32 vcc, 0, v0
	s_and_saveexec_b64 s[16:17], vcc
	s_cbranch_execz .LBB0_2625
	s_mov_b64 s[42:43], exec
	v_mbcnt_lo_u32_b32 v0, s42, 0
	v_mbcnt_hi_u32_b32 v0, s43, v0
	v_cmp_eq_u32_e32 vcc, 0, v0
	s_and_saveexec_b64 s[22:23], vcc
	s_cbranch_execz .LBB0_2624
	s_cmp_lg_u32 s98, 0
	s_cbranch_scc1 .Lpfq_have_mla
	s_bcnt1_i32_b64 s6, s[42:43]
	v_mov_b32_e32 v2, s6
	global_atomic_add v2, v1, v2, s[14:15] offset:192 sc0
	s_waitcnt vmcnt(0)
	s_branch .Lpfq_join_mla
.Lpfq_have_mla:
	s_waitcnt vmcnt(16)
	v_mov_b32_e32 v2, v230

.LBB0_2624:
	s_or_b64 exec, exec, s[22:23]
	v_readfirstlane_b32 s6, v2
	v_mov_b32_e32 v2, s13
	s_nop 0
	v_add_u32_e32 v0, s6, v0
	ds_write_b32 v2, v0

.LBB0_2626:
	s_waitcnt lgkmcnt(0)
	s_barrier
	ds_read_b32 v0, v192
	s_mov_b64 s[16:17], -1
	s_waitcnt lgkmcnt(0)
	v_cmp_lt_i32_e32 vcc, s29, v0
	v_readfirstlane_b32 s6, v0
	s_cbranch_vccnz .LBB0_2619
	s_lshl_b32 s17, s6, 5
	s_and_b32 s17, s17, 0x380
	s_lshl_b32 s8, s6, 3
	s_and_b32 s16, s6, 0x60
	s_or_b32 s6, s17, s6
	s_ashr_i32 s57, s6, 7
	s_sub_i32 s43, 7, s57
	s_lshl_b32 s23, s43, 8
	s_and_b32 s9, s8, 16
	v_mbcnt_lo_u32_b32 v6, -1, 0
	v_mbcnt_hi_u32_b32 v6, -1, v6
	s_add_i32 s23, s23, s47
	v_and_b32_e32 v4, 31, v6
	s_or_b32 s9, s9, s16
	s_and_b32 s6, s8, 8
	v_or_b32_e32 v185, s23, v4
	s_or_b32 s22, s6, s56
	v_ashrrev_i32_e32 v5, 5, v6
	v_lshl_add_u32 v184, s9, 7, v185
	v_mov_b64_e32 v[2:3], s[18:19]
	v_mad_i64_i32 v[2:3], s[16:17], v184, s30, v[2:3]
	s_mul_i32 s6, s22, 0x180
	v_lshlrev_b32_e32 v8, 3, v5
	v_lshl_add_u64 v[2:3], v[2:3], 0, s[6:7]
	v_ashrrev_i32_e32 v9, 31, v8
	v_lshl_add_u64 v[8:9], v[8:9], 1, v[2:3]
	global_load_dwordx4 v[112:115], v[8:9], off
	global_load_dwordx4 v[116:119], v[8:9], off offset:32
	global_load_dwordx4 v[120:123], v[8:9], off offset:64
	global_load_dwordx4 v[124:127], v[8:9], off offset:96
	global_load_dwordx4 v[128:131], v[8:9], off offset:128
	global_load_dwordx4 v[132:135], v[8:9], off offset:160
	global_load_dwordx4 v[136:139], v[8:9], off offset:192
	global_load_dwordx4 v[140:143], v[8:9], off offset:224
	s_lshl_b32 s6, s9, 20
	s_add_u32 s6, s20, s6
	v_add_u32_e32 v0, s91, v6
	s_addc_u32 s8, s21, 0
	s_lshl_b32 s16, s22, 9
	v_lshlrev_b32_e32 v2, 4, v6
	s_add_u32 s60, s6, s16
	v_ashrrev_i32_e32 v7, 4, v0
	v_and_b32_e32 v187, 0xf0, v2
	s_addc_u32 s61, s8, 0
	v_ashrrev_i32_e32 v3, 3, v0
	v_lshl_or_b32 v0, v7, 13, v187
	global_load_dwordx4 v[160:163], v0, s[60:61]
	v_lshl_add_u64 v[188:189], s[60:61], 0, v[0:1]
	s_lshl_b32 s6, s9, 14
	v_add_co_u32_e32 v10, vcc, s34, v188
	s_add_u32 s16, s62, s6
	v_and_b32_e32 v194, 0x70, v2
	v_addc_co_u32_e32 v11, vcc, 0, v189, vcc
	s_addc_u32 s17, s63, 0
	v_lshl_or_b32 v2, v3, 7, v194
	global_load_dwordx4 v[168:171], v[10:11], off
	global_load_dwordx4 v[164:167], v2, s[16:17]
	global_load_dwordx4 v[172:175], v0, s[60:61] offset:256
	global_load_dwordx4 v[176:179], v[10:11], off offset:256
	global_load_dwordx4 v[144:147], v[8:9], off offset:256
	global_load_dwordx4 v[148:151], v[8:9], off offset:288
	global_load_dwordx4 v[152:155], v[8:9], off offset:320
	global_load_dwordx4 v[156:159], v[8:9], off offset:352
	v_mul_lo_u32 v195, v7, s35
	v_lshlrev_b32_e32 v186, 2, v5
	v_mul_lo_u32 v196, v3, s35
	v_mul_lo_u32 v0, v7, s44
	v_add3_u32 v3, 0, v195, v187
	s_cmp_gt_i32 s57, 7
	v_add3_u32 v8, 0, v196, v194
	v_add_u32_e32 v9, v3, v0
	v_add3_u32 v0, v3, s45, v0
	s_waitcnt vmcnt(8)
	ds_write_b128 v3, v[160:163]
	s_waitcnt vmcnt(7)
	ds_write_b128 v3, v[168:171] offset:12800
	s_waitcnt vmcnt(6)
	ds_write_b128 v8, v[164:167] offset:256
	s_waitcnt vmcnt(5)
	ds_write_b128 v9, v[172:175] offset:25600
	s_waitcnt vmcnt(0)
	ds_write_b128 v0, v[176:179] offset:23040
	s_waitcnt lgkmcnt(0)
	s_barrier
	s_cbranch_scc1 .LBB0_2617
	v_mov_b32_e32 v3, v1
	v_lshrrev_b32_e32 v0, 2, v6
	v_lshl_add_u64 v[190:191], s[16:17], 0, v[2:3]
	v_and_or_b32 v0, v0, 3, v186
	v_lshlrev_b32_e32 v2, 1, v6
	v_lshlrev_b32_e32 v3, 3, v6
	v_and_b32_e32 v197, 32, v2
	v_mul_lo_u32 v198, v0, s46
	s_lshl_b32 s6, s43, 2
	v_lshlrev_b32_e32 v0, 7, v5
	v_lshlrev_b32_e32 v2, 2, v4
	v_mov_b32_e32 v14, v1
	v_mov_b32_e32 v15, v1
	v_and_b32_e32 v199, 24, v3
	v_mul_lo_u32 v201, v7, s46
	v_mul_u32_u24_e32 v203, 0x190, v4
	v_lshlrev_b32_e32 v204, 4, v5
	v_bitop3_b32 v205, v0, s48, v2 bitop3:0x36
	s_or_b32 s43, s6, 3
	s_lshl_b32 s6, s57, 2
	v_mov_b32_e32 v0, v1
	v_mov_b32_e32 v2, v1
	v_mov_b32_e32 v3, v1
	v_mov_b32_e32 v4, v1
	v_mov_b32_e32 v5, v1
	v_mov_b32_e32 v6, v1
	v_mov_b32_e32 v7, v1
	v_mov_b32_e32 v8, v1
	v_mov_b32_e32 v9, v1
	v_mov_b32_e32 v10, v1
	v_mov_b32_e32 v11, v1
	v_mov_b32_e32 v12, v1
	v_mov_b32_e32 v13, v1
	v_mov_b64_e32 v[30:31], v[14:15]
	v_mov_b64_e32 v[46:47], v[14:15]
	v_mov_b64_e32 v[62:63], v[14:15]
	v_mov_b64_e32 v[78:79], v[14:15]
	v_add_u32_e32 v200, 0x3200, v195
	v_add_u32_e32 v202, 0x2800, v201
	s_or_b32 s42, s23, 31
	s_and_b64 vcc, exec, s[4:5]
	s_cbranch_vccnz .Lpfq_skip_mla
	v_mbcnt_lo_u32_b32 v229, -1, 0
	v_mbcnt_hi_u32_b32 v229, -1, v229
	v_cmp_eq_u32_e32 vcc, 0, v229
	s_and_saveexec_b64 s[100:101], vcc
	v_mov_b32_e32 v230, 1
	global_atomic_add v230, v229, v230, s[14:15] offset:192 sc0
	s_mov_b64 exec, s[100:101]
	s_mov_b32 s98, 1
.Lpfq_skip_mla:
	s_sub_i32 s57, 32, s6
	s_mov_b32 s64, 0
	v_mov_b32_e32 v206, 0
	v_mov_b32_e32 v207, 0xf149f2ca
	v_mov_b64_e32 v[28:29], v[12:13]
	v_mov_b64_e32 v[26:27], v[10:11]
	v_mov_b64_e32 v[24:25], v[8:9]
	v_mov_b64_e32 v[22:23], v[6:7]
	v_mov_b64_e32 v[20:21], v[4:5]
	v_mov_b64_e32 v[18:19], v[2:3]
	v_mov_b64_e32 v[16:17], v[0:1]
	v_mov_b64_e32 v[44:45], v[12:13]
	v_mov_b64_e32 v[42:43], v[10:11]
	v_mov_b64_e32 v[40:41], v[8:9]
	v_mov_b64_e32 v[38:39], v[6:7]
	v_mov_b64_e32 v[36:37], v[4:5]
	v_mov_b64_e32 v[34:35], v[2:3]
	v_mov_b64_e32 v[32:33], v[0:1]
	v_mov_b64_e32 v[60:61], v[12:13]
	v_mov_b64_e32 v[58:59], v[10:11]
	v_mov_b64_e32 v[56:57], v[8:9]
	v_mov_b64_e32 v[54:55], v[6:7]
	v_mov_b64_e32 v[52:53], v[4:5]
	v_mov_b64_e32 v[50:51], v[2:3]
	v_mov_b64_e32 v[48:49], v[0:1]
	v_mov_b64_e32 v[76:77], v[12:13]
	v_mov_b64_e32 v[74:75], v[10:11]
	v_mov_b64_e32 v[72:73], v[8:9]
	v_mov_b64_e32 v[70:71], v[6:7]
	v_mov_b64_e32 v[68:69], v[4:5]
	v_mov_b64_e32 v[66:67], v[2:3]
	v_mov_b64_e32 v[64:65], v[0:1]
	s_mov_b32 s65, 0
	s_cmp_lt_i32 s65, s43
	s_cselect_b64 s[16:17], -1, 0
	s_cmp_ge_i32 s65, s43
	s_cbranch_scc1 .LBB0_2630

	.amdhsa_kernel _Z10fwd_kernel4Ptrs
		.amdhsa_group_segment_fixed_size 0
		.amdhsa_private_segment_fixed_size 0
		.amdhsa_kernarg_size 456
		.amdhsa_user_sgpr_count 2
		.amdhsa_user_sgpr_dispatch_ptr 0
		.amdhsa_user_sgpr_queue_ptr 0
		.amdhsa_user_sgpr_kernarg_segment_ptr 1
		.amdhsa_user_sgpr_dispatch_id 0
		.amdhsa_user_sgpr_kernarg_preload_length 0
		.amdhsa_user_sgpr_kernarg_preload_offset 0
		.amdhsa_user_sgpr_private_segment_size 0
		.amdhsa_uses_dynamic_stack 0
		.amdhsa_enable_private_segment 0
		.amdhsa_system_sgpr_workgroup_id_x 1
		.amdhsa_system_sgpr_workgroup_id_y 0
		.amdhsa_system_sgpr_workgroup_id_z 0
		.amdhsa_system_sgpr_workgroup_info 0
		.amdhsa_system_vgpr_workitem_id 2
		.amdhsa_next_free_vgpr 256
		.amdhsa_next_free_sgpr 102
		.amdhsa_accum_offset 256
		.amdhsa_reserve_vcc 1
		.amdhsa_float_round_mode_32 0
		.amdhsa_float_round_mode_16_64 0
		.amdhsa_float_denorm_mode_32 3
		.amdhsa_float_denorm_mode_16_64 3
		.amdhsa_dx10_clamp 1
		.amdhsa_ieee_mode 1
		.amdhsa_fp16_overflow 0
		.amdhsa_tg_split 0
		.amdhsa_exception_fp_ieee_invalid_op 0
		.amdhsa_exception_fp_denorm_src 0
		.amdhsa_exception_fp_ieee_div_zero 0
		.amdhsa_exception_fp_ieee_overflow 0
		.amdhsa_exception_fp_ieee_underflow 0
		.amdhsa_exception_fp_ieee_inexact 0
		.amdhsa_exception_int_div_zero 0
	.end_amdhsa_kernel

amdhsa.kernels:
  - .agpr_count:     0
    .args:
      - .offset:         0
        .size:           200
        .value_kind:     by_value
      - .offset:         200
        .size:           4
        .value_kind:     hidden_block_count_x
      - .offset:         204
        .size:           4
        .value_kind:     hidden_block_count_y
      - .offset:         208
        .size:           4
        .value_kind:     hidden_block_count_z
      - .offset:         212
        .size:           2
        .value_kind:     hidden_group_size_x
      - .offset:         214
        .size:           2
        .value_kind:     hidden_group_size_y
      - .offset:         216
        .size:           2
        .value_kind:     hidden_group_size_z
      - .offset:         218
        .size:           2
        .value_kind:     hidden_remainder_x
      - .offset:         220
        .size:           2
        .value_kind:     hidden_remainder_y
      - .offset:         222
        .size:           2
        .value_kind:     hidden_remainder_z
      - .offset:         240
        .size:           8
        .value_kind:     hidden_global_offset_x
      - .offset:         248
        .size:           8
        .value_kind:     hidden_global_offset_y
      - .offset:         256
        .size:           8
        .value_kind:     hidden_global_offset_z
      - .offset:         264
        .size:           2
        .value_kind:     hidden_grid_dims
      - .offset:         288
        .size:           8
        .value_kind:     hidden_multigrid_sync_arg
      - .offset:         320
        .size:           4
        .value_kind:     hidden_dynamic_lds_size
    .group_segment_fixed_size: 0
    .kernarg_segment_align: 8
    .kernarg_segment_size: 456
    .language:       OpenCL C
    .language_version:
      - 2
      - 0
    .max_flat_workgroup_size: 512
    .name:           _Z10fwd_kernel4Ptrs
    .private_segment_fixed_size: 0
    .sgpr_count:     108
    .sgpr_spill_count: 24
    .symbol:         _Z10fwd_kernel4Ptrs.kd
    .uniform_work_group_size: 1
    .uses_dynamic_stack: false
    .vgpr_count:     256
    .vgpr_spill_count: 0
    .wavefront_size: 64
